# latent attention PV sections: counted per-MFMA lgkmcnt waits (6,6,6,6 ... 6,4,2,0) instead of lgkmcnt(0) per group of four
# speedup vs baseline: 1.0030x; 1.0030x over previous
.LBB0_709:
	s_add_i32 s20, s85, -3
	ds_read_b128 v[64:67], v204 offset:49152
	ds_read_b128 v[68:71], v204 offset:57344
	ds_read_b128 v[178:181], v207 offset:49152
	ds_read_b128 v[182:185], v207 offset:57344
	v_exp_f32_e32 v144, v158
	v_exp_f32_e32 v158, v159
	s_waitcnt lgkmcnt(3)
	v_mfma_f32_32x32x16_bf16 v[80:95], v[64:67], v[124:127], 0
	v_exp_f32_e32 v159, v160
	v_add_f32_e32 v160, 0, v216
	v_add_f32_e32 v160, v230, v160
	v_add_f32_e32 v160, v174, v160
	v_add_f32_e32 v160, v219, v160
	v_add_f32_e32 v160, v173, v160
	v_add_f32_e32 v160, v175, v160
	s_waitcnt lgkmcnt(2)
	v_mfma_f32_32x32x16_bf16 v[64:79], v[68:71], v[124:127], 0
	v_add_f32_e32 v160, v163, v160
	v_add_f32_e32 v160, v172, v160
	v_add_f32_e32 v160, v164, v160
	v_add_f32_e32 v160, v171, v160
	v_add_f32_e32 v160, v165, v160
	v_add_f32_e32 v160, v170, v160
	v_add_f32_e32 v160, v166, v160
	s_waitcnt lgkmcnt(1)
	v_mfma_f32_32x32x16_bf16 v[80:95], v[178:181], v[120:123], v[80:95]
	v_add_f32_e32 v160, v169, v160
	v_exp_f32_e32 v156, v156
	v_add_f32_e32 v160, v145, v160
	v_exp_f32_e32 v157, v157
	v_add_f32_e32 v160, v167, v160
	v_exp_f32_e32 v150, v150
	v_add_f32_e32 v160, v144, v160
	s_waitcnt lgkmcnt(0)
	v_mfma_f32_32x32x16_bf16 v[64:79], v[182:185], v[120:123], v[64:79]
	ds_read_b128 v[178:181], v209 offset:49152
	ds_read_b128 v[182:185], v209 offset:57344
	v_exp_f32_e32 v151, v151
	v_add_f32_e32 v160, v158, v160
	v_exp_f32_e32 v148, v148
	v_add_f32_e32 v160, v156, v160
	v_exp_f32_e32 v149, v149
	v_add_f32_e32 v160, v157, v160
	s_waitcnt lgkmcnt(1)
	v_mfma_f32_32x32x16_bf16 v[80:95], v[178:181], v[116:119], v[80:95]
	v_exp_f32_e32 v146, v146
	v_add_f32_e32 v160, v150, v160
	v_exp_f32_e32 v147, v147
	v_add_f32_e32 v160, v151, v160
	v_add_f32_e32 v160, v148, v160
	v_add_f32_e32 v160, v149, v160
	v_exp_f32_e32 v154, v154
	s_waitcnt lgkmcnt(0)
	v_mfma_f32_32x32x16_bf16 v[64:79], v[182:185], v[116:119], v[64:79]
	ds_read_b128 v[178:181], v205 offset:49152
	ds_read_b128 v[182:185], v205 offset:57344
	v_add_f32_e32 v160, v146, v160
	v_exp_f32_e32 v155, v155
	v_add_f32_e32 v160, v147, v160
	v_exp_f32_e32 v152, v152
	v_add_f32_e32 v160, v159, v160
	v_exp_f32_e32 v153, v153
	s_waitcnt lgkmcnt(1)
	v_mfma_f32_32x32x16_bf16 v[80:95], v[178:181], v[112:115], v[80:95]
	s_waitcnt lgkmcnt(0)
	v_mfma_f32_32x32x16_bf16 v[64:79], v[182:185], v[112:115], v[64:79]
	ds_read_b128 v[178:181], v206 offset:49152
	ds_read_b128 v[182:185], v206 offset:57344
	s_waitcnt lgkmcnt(1)
	v_mfma_f32_32x32x16_bf16 v[80:95], v[178:181], v[108:111], v[80:95]
	s_waitcnt lgkmcnt(0)
	v_mfma_f32_32x32x16_bf16 v[64:79], v[182:185], v[108:111], v[64:79]
	ds_read_b128 v[178:181], v208 offset:49152
	ds_read_b128 v[182:185], v208 offset:57344
	s_waitcnt lgkmcnt(1)
	v_mfma_f32_32x32x16_bf16 v[80:95], v[178:181], v[104:107], v[80:95]
	s_waitcnt lgkmcnt(0)
	v_mfma_f32_32x32x16_bf16 v[64:79], v[182:185], v[104:107], v[64:79]
	ds_read_b128 v[178:181], v210 offset:49152
	ds_read_b128 v[182:185], v210 offset:57344
	s_waitcnt lgkmcnt(1)
	v_mfma_f32_32x32x16_bf16 v[80:95], v[178:181], v[100:103], v[80:95]
	s_waitcnt lgkmcnt(0)
	v_mfma_f32_32x32x16_bf16 v[64:79], v[182:185], v[100:103], v[64:79]
	ds_read_b128 v[178:181], v211 offset:49152
	ds_read_b128 v[182:185], v211 offset:57344
	s_waitcnt lgkmcnt(1)
	v_mfma_f32_32x32x16_bf16 v[80:95], v[178:181], v[96:99], v[80:95]
	v_exp_f32_e32 v179, v161
	s_nop 0
	v_add_f32_e32 v160, v179, v160
	v_add_f32_e32 v160, v154, v160
	v_add_f32_e32 v160, v155, v160
	s_waitcnt lgkmcnt(0)
	v_mfma_f32_32x32x16_bf16 v[64:79], v[182:185], v[96:99], v[64:79]
	v_add_f32_e32 v160, v152, v160
	v_add_f32_e32 v213, v153, v160
	v_mov_b32_e32 v214, v213
	v_cvt_pk_bf16_f32 v160, v216, v230
	v_cvt_pk_bf16_f32 v161, v174, v219
	v_cvt_pk_bf16_f32 v162, v173, v175
	s_nop 1
	v_permlane32_swap_b32_e32 v213, v214
	v_cvt_pk_bf16_f32 v163, v163, v172
	v_permlane32_swap_b32_e32 v160, v162
	v_cvt_pk_bf16_f32 v164, v164, v171
	v_cvt_pk_bf16_f32 v165, v165, v170
	v_cvt_pk_bf16_f32 v166, v166, v169
	v_cvt_pk_bf16_f32 v167, v145, v167
	v_cvt_pk_bf16_f32 v170, v144, v158
	v_cvt_pk_bf16_f32 v171, v156, v157
	v_cvt_pk_bf16_f32 v172, v150, v151
	v_cvt_pk_bf16_f32 v173, v148, v149
	v_cvt_pk_bf16_f32 v178, v146, v147
	v_cvt_pk_bf16_f32 v179, v159, v179
	v_cvt_pk_bf16_f32 v180, v154, v155
	v_cvt_pk_bf16_f32 v181, v152, v153
	v_permlane32_swap_b32_e32 v161, v163
	v_permlane32_swap_b32_e32 v164, v166
	v_permlane32_swap_b32_e32 v165, v167
	v_permlane32_swap_b32_e32 v170, v172
	v_permlane32_swap_b32_e32 v171, v173
	v_permlane32_swap_b32_e32 v178, v180
	v_permlane32_swap_b32_e32 v179, v181
	s_cmp_lt_u32 s20, 6
	s_cselect_b64 s[4:5], -1, 0
	s_and_b64 s[18:19], s[4:5], exec
	s_cselect_b32 s16, 0, -8
	s_add_i32 s16, s16, s85
	s_add_i32 s16, s16, -1
	s_and_b64 s[4:5], s[4:5], exec
	s_cselect_b32 s19, s49, s43
	s_cselect_b32 s18, s48, s36
	s_cselect_b32 s21, s57, s52
	s_cselect_b32 s22, s56, s44
	s_lshl_b64 s[4:5], s[16:17], 16
	s_add_u32 s18, s18, s4
	s_addc_u32 s19, s19, s5
	s_add_u32 s4, s22, s4
	s_addc_u32 s5, s21, s5
	global_load_dwordx4 v[144:147], v222, s[4:5]
	global_load_dwordx4 v[148:151], v243, s[4:5]
	global_load_dwordx4 v[152:155], v222, s[18:19]
	global_load_dwordx4 v[156:159], v243, s[18:19]
	ds_read_b64_tr_b16 v[182:183], v199 offset:0
	ds_read_b64_tr_b16 v[184:185], v199 offset:0x800
	ds_read_b64_tr_b16 v[216:217], v199 offset:0x1000
	ds_read_b64_tr_b16 v[218:219], v199 offset:0x1800
	ds_read_b64_tr_b16 v[230:231], v199 offset:0x2000
	ds_read_b64_tr_b16 v[232:233], v199 offset:0x2800
	ds_read_b64_tr_b16 v[234:235], v199 offset:0x3000
	ds_read_b64_tr_b16 v[236:237], v199 offset:0x3800
	s_nop 0
	s_waitcnt lgkmcnt(6)
	v_mfma_f32_32x32x16_bf16 v[0:15], v[160:163], v[182:185], v[0:15]
	ds_read_b64_tr_b16 v[182:183], v199 offset:0x200
	ds_read_b64_tr_b16 v[184:185], v199 offset:0xa00
	s_waitcnt lgkmcnt(6)
	v_mfma_f32_32x32x16_bf16 v[0:15], v[164:167], v[216:219], v[0:15]
	ds_read_b64_tr_b16 v[216:217], v199 offset:0x1200
	ds_read_b64_tr_b16 v[218:219], v199 offset:0x1a00
	s_waitcnt lgkmcnt(6)
	v_mfma_f32_32x32x16_bf16 v[0:15], v[170:173], v[230:233], v[0:15]
	ds_read_b64_tr_b16 v[230:231], v199 offset:0x2200
	ds_read_b64_tr_b16 v[232:233], v199 offset:0x2a00
	s_waitcnt lgkmcnt(6)
	v_mfma_f32_32x32x16_bf16 v[0:15], v[178:181], v[234:237], v[0:15]
	ds_read_b64_tr_b16 v[234:235], v199 offset:0x3200
	ds_read_b64_tr_b16 v[236:237], v199 offset:0x3a00
	s_waitcnt lgkmcnt(6)
	v_mfma_f32_32x32x16_bf16 v[48:63], v[160:163], v[182:185], v[48:63]
	ds_read_b64_tr_b16 v[182:183], v199 offset:0x400
	ds_read_b64_tr_b16 v[184:185], v199 offset:0xc00
	s_waitcnt lgkmcnt(6)
	v_mfma_f32_32x32x16_bf16 v[48:63], v[164:167], v[216:219], v[48:63]
	ds_read_b64_tr_b16 v[216:217], v199 offset:0x1400
	ds_read_b64_tr_b16 v[218:219], v199 offset:0x1c00
	s_waitcnt lgkmcnt(6)
	v_mfma_f32_32x32x16_bf16 v[48:63], v[170:173], v[230:233], v[48:63]
	ds_read_b64_tr_b16 v[230:231], v199 offset:0x2400
	ds_read_b64_tr_b16 v[232:233], v199 offset:0x2c00
	s_waitcnt lgkmcnt(6)
	v_mfma_f32_32x32x16_bf16 v[48:63], v[178:181], v[234:237], v[48:63]
	ds_read_b64_tr_b16 v[234:235], v199 offset:0x3400
	ds_read_b64_tr_b16 v[236:237], v199 offset:0x3c00
	s_waitcnt lgkmcnt(6)
	v_mfma_f32_32x32x16_bf16 v[32:47], v[160:163], v[182:185], v[32:47]
	ds_read_b64_tr_b16 v[182:183], v199 offset:0x600
	ds_read_b64_tr_b16 v[184:185], v199 offset:0xe00
	s_waitcnt lgkmcnt(6)
	v_mfma_f32_32x32x16_bf16 v[32:47], v[164:167], v[216:219], v[32:47]
	ds_read_b64_tr_b16 v[216:217], v199 offset:0x1600
	ds_read_b64_tr_b16 v[218:219], v199 offset:0x1e00
	s_waitcnt lgkmcnt(6)
	v_mfma_f32_32x32x16_bf16 v[32:47], v[170:173], v[230:233], v[32:47]
	ds_read_b64_tr_b16 v[230:231], v199 offset:0x2600
	ds_read_b64_tr_b16 v[232:233], v199 offset:0x2e00
	s_waitcnt lgkmcnt(6)
	v_mfma_f32_32x32x16_bf16 v[32:47], v[178:181], v[234:237], v[32:47]
	ds_read_b64_tr_b16 v[234:235], v199 offset:0x3600
	ds_read_b64_tr_b16 v[236:237], v199 offset:0x3e00
	s_waitcnt lgkmcnt(6)
	v_mfma_f32_32x32x16_bf16 v[16:31], v[160:163], v[182:185], v[16:31]
	v_max_f32_e32 v160, v81, v81
	v_max_f32_e32 v161, v80, v80
	v_max_f32_e32 v160, v161, v160
	v_max3_f32 v160, v160, v82, v83
	v_max3_f32 v160, v160, v84, v85
	v_max3_f32 v160, v160, v86, v87
	v_max3_f32 v160, v160, v88, v89
	v_max3_f32 v160, v160, v90, v91
	v_max3_f32 v160, v160, v92, v93
	s_waitcnt lgkmcnt(4)
	v_mfma_f32_32x32x16_bf16 v[16:31], v[164:167], v[216:219], v[16:31]
	v_max3_f32 v160, v160, v94, v95
	v_max3_f32 v160, v160, v64, v65
	v_max3_f32 v160, v160, v66, v67
	v_max3_f32 v160, v160, v68, v69
	v_max3_f32 v160, v160, v70, v71
	v_max3_f32 v160, v160, v72, v73
	v_max3_f32 v160, v160, v74, v75
	v_max3_f32 v160, v160, v76, v77
	s_waitcnt lgkmcnt(2)
	v_mfma_f32_32x32x16_bf16 v[16:31], v[170:173], v[230:233], v[16:31]
	v_max3_f32 v160, v160, v78, v79
	v_mov_b32_e32 v161, v160
	s_nop 1
	v_permlane32_swap_b32_e32 v160, v161
	v_max_f32_e32 v161, v161, v161
	v_max_f32_e32 v160, v160, v160
	v_max_f32_e32 v160, v160, v161
	v_sub_f32_e32 v161, v160, v168
	v_cmp_ge_f32_e32 vcc, s14, v161
	v_max_f32_e32 v161, v168, v168
	v_max_f32_e32 v160, v161, v160
	s_waitcnt lgkmcnt(0)
	v_mfma_f32_32x32x16_bf16 v[16:31], v[178:181], v[234:237], v[16:31]
	v_sub_f32_e32 v161, v168, v160
	v_mul_f32_e32 v161, 0x3e0293ee, v161
	v_exp_f32_e32 v161, v161
	s_cmp_eq_u64 vcc, exec
	s_cselect_b64 s[4:5], -1, 0
	s_barrier
	s_waitcnt vmcnt(4)
	v_cndmask_b32_e64 v215, v161, 1.0, s[4:5]
	v_cmp_gt_f32_e32 vcc, 1.0, v215
	s_waitcnt vmcnt(4)
	ds_write_b128 v200, v[128:131]
	ds_write_b128 v201, v[132:135]
	ds_write_b128 v202, v[136:139] offset:32768
	ds_write_b128 v203, v[140:143] offset:32768
	s_cbranch_vccz .LBB0_713
	s_and_saveexec_b64 s[18:19], s[2:3]
	ds_write_b32 v189, v215 offset:128
	s_or_b64 exec, exec, s[18:19]
	s_waitcnt lgkmcnt(0)
	v_add_u32_e32 v161, v191, v190
	ds_read_b128 v[162:165], v161 offset:224
	ds_read_b128 v[170:173], v161 offset:192
	ds_read_b128 v[178:181], v161 offset:160
	ds_read_b128 v[182:185], v161 offset:128
	s_waitcnt lgkmcnt(3)
	v_pk_mul_f32 v[12:13], v[12:13], v[162:163]
	s_waitcnt lgkmcnt(2)
	v_pk_mul_f32 v[8:9], v[8:9], v[170:171]
	s_waitcnt lgkmcnt(1)
	v_pk_mul_f32 v[4:5], v[4:5], v[178:179]
	v_pk_mul_f32 v[14:15], v[14:15], v[164:165]
	v_pk_mul_f32 v[10:11], v[10:11], v[172:173]
	v_pk_mul_f32 v[6:7], v[6:7], v[180:181]
	s_waitcnt lgkmcnt(0)
	v_pk_mul_f32 v[2:3], v[2:3], v[184:185]
	v_pk_mul_f32 v[0:1], v[0:1], v[182:183]
	v_pk_mul_f32 v[60:61], v[60:61], v[162:163]
	v_pk_mul_f32 v[56:57], v[56:57], v[170:171]
	v_pk_mul_f32 v[52:53], v[52:53], v[178:179]
	v_pk_mul_f32 v[62:63], v[62:63], v[164:165]
	v_pk_mul_f32 v[58:59], v[58:59], v[172:173]
	v_pk_mul_f32 v[54:55], v[54:55], v[180:181]
	v_pk_mul_f32 v[50:51], v[50:51], v[184:185]
	v_pk_mul_f32 v[48:49], v[48:49], v[182:183]
	v_pk_mul_f32 v[44:45], v[44:45], v[162:163]
	v_pk_mul_f32 v[40:41], v[40:41], v[170:171]
	v_pk_mul_f32 v[36:37], v[36:37], v[178:179]
	v_pk_mul_f32 v[46:47], v[46:47], v[164:165]
	v_pk_mul_f32 v[42:43], v[42:43], v[172:173]
	v_pk_mul_f32 v[38:39], v[38:39], v[180:181]
	v_pk_mul_f32 v[34:35], v[34:35], v[184:185]
	v_pk_mul_f32 v[32:33], v[32:33], v[182:183]
	v_pk_mul_f32 v[28:29], v[28:29], v[162:163]
	v_pk_mul_f32 v[24:25], v[24:25], v[170:171]
	v_pk_mul_f32 v[20:21], v[20:21], v[178:179]
	v_pk_mul_f32 v[30:31], v[30:31], v[164:165]
	v_pk_mul_f32 v[26:27], v[26:27], v[172:173]
	v_pk_mul_f32 v[22:23], v[22:23], v[180:181]
	v_pk_mul_f32 v[18:19], v[18:19], v[184:185]
	v_pk_mul_f32 v[16:17], v[16:17], v[182:183]

.LBB0_715:
	ds_read_b64_tr_b16 v[178:179], v198 offset:0
	ds_read_b64_tr_b16 v[180:181], v198 offset:0x800
	ds_read_b64_tr_b16 v[182:183], v198 offset:0x1000
	ds_read_b64_tr_b16 v[184:185], v198 offset:0x1800
	ds_read_b64_tr_b16 v[230:231], v198 offset:0x2000
	ds_read_b64_tr_b16 v[232:233], v198 offset:0x2800
	ds_read_b64_tr_b16 v[234:235], v198 offset:0x3000
	ds_read_b64_tr_b16 v[236:237], v198 offset:0x3800
	s_nop 0
	s_waitcnt lgkmcnt(6)
	v_mfma_f32_32x32x16_bf16 v[0:15], v[160:163], v[178:181], v[0:15]
	ds_read_b64_tr_b16 v[178:179], v198 offset:0x200
	ds_read_b64_tr_b16 v[180:181], v198 offset:0xa00
	s_waitcnt lgkmcnt(6)
	v_mfma_f32_32x32x16_bf16 v[0:15], v[164:167], v[182:185], v[0:15]
	ds_read_b64_tr_b16 v[182:183], v198 offset:0x1200
	ds_read_b64_tr_b16 v[184:185], v198 offset:0x1a00
	s_waitcnt lgkmcnt(6)
	v_mfma_f32_32x32x16_bf16 v[0:15], v[168:171], v[230:233], v[0:15]
	ds_read_b64_tr_b16 v[230:231], v198 offset:0x2200
	ds_read_b64_tr_b16 v[232:233], v198 offset:0x2a00
	s_waitcnt lgkmcnt(6)
	v_mfma_f32_32x32x16_bf16 v[0:15], v[172:175], v[234:237], v[0:15]
	ds_read_b64_tr_b16 v[234:235], v198 offset:0x3200
	ds_read_b64_tr_b16 v[236:237], v198 offset:0x3a00
	s_waitcnt lgkmcnt(6)
	v_mfma_f32_32x32x16_bf16 v[48:63], v[160:163], v[178:181], v[48:63]
	ds_read_b64_tr_b16 v[178:179], v198 offset:0x400
	ds_read_b64_tr_b16 v[180:181], v198 offset:0xc00
	s_waitcnt lgkmcnt(6)
	v_mfma_f32_32x32x16_bf16 v[48:63], v[164:167], v[182:185], v[48:63]
	ds_read_b64_tr_b16 v[182:183], v198 offset:0x1400
	ds_read_b64_tr_b16 v[184:185], v198 offset:0x1c00
	s_waitcnt lgkmcnt(6)
	v_mfma_f32_32x32x16_bf16 v[48:63], v[168:171], v[230:233], v[48:63]
	ds_read_b64_tr_b16 v[230:231], v198 offset:0x2400
	ds_read_b64_tr_b16 v[232:233], v198 offset:0x2c00
	s_waitcnt lgkmcnt(6)
	v_mfma_f32_32x32x16_bf16 v[48:63], v[172:175], v[234:237], v[48:63]
	ds_read_b64_tr_b16 v[234:235], v198 offset:0x3400
	ds_read_b64_tr_b16 v[236:237], v198 offset:0x3c00
	s_waitcnt lgkmcnt(6)
	v_mfma_f32_32x32x16_bf16 v[32:47], v[160:163], v[178:181], v[32:47]
	ds_read_b64_tr_b16 v[178:179], v198 offset:0x600
	ds_read_b64_tr_b16 v[180:181], v198 offset:0xe00
	s_waitcnt lgkmcnt(6)
	v_mfma_f32_32x32x16_bf16 v[32:47], v[164:167], v[182:185], v[32:47]
	ds_read_b64_tr_b16 v[182:183], v198 offset:0x1600
	ds_read_b64_tr_b16 v[184:185], v198 offset:0x1e00
	s_waitcnt lgkmcnt(6)
	v_mfma_f32_32x32x16_bf16 v[32:47], v[168:171], v[230:233], v[32:47]
	ds_read_b64_tr_b16 v[230:231], v198 offset:0x2600
	ds_read_b64_tr_b16 v[232:233], v198 offset:0x2e00
	s_waitcnt lgkmcnt(6)
	v_mfma_f32_32x32x16_bf16 v[32:47], v[172:175], v[234:237], v[32:47]
	ds_read_b64_tr_b16 v[234:235], v198 offset:0x3600
	ds_read_b64_tr_b16 v[236:237], v198 offset:0x3e00
	s_waitcnt lgkmcnt(6)
	v_mfma_f32_32x32x16_bf16 v[16:31], v[160:163], v[178:181], v[16:31]
	v_max_f32_e32 v160, v81, v81
	v_max_f32_e32 v161, v80, v80
	v_max_f32_e32 v160, v161, v160
	v_max3_f32 v160, v160, v82, v83
	v_max3_f32 v160, v160, v84, v85
	v_max3_f32 v160, v160, v86, v87
	v_max3_f32 v160, v160, v88, v89
	v_max3_f32 v160, v160, v90, v91
	v_max3_f32 v160, v160, v92, v93
	s_waitcnt lgkmcnt(4)
	v_mfma_f32_32x32x16_bf16 v[16:31], v[164:167], v[182:185], v[16:31]
	v_max3_f32 v160, v160, v94, v95
	v_max3_f32 v160, v160, v64, v65
	v_max3_f32 v160, v160, v66, v67
	v_max3_f32 v160, v160, v68, v69
	v_max3_f32 v160, v160, v70, v71
	v_max3_f32 v160, v160, v72, v73
	v_max3_f32 v160, v160, v74, v75
	v_max3_f32 v160, v160, v76, v77
	s_waitcnt lgkmcnt(2)
	v_mfma_f32_32x32x16_bf16 v[16:31], v[168:171], v[230:233], v[16:31]
	v_max3_f32 v160, v160, v78, v79
	v_mov_b32_e32 v161, v160
	s_nop 1
	v_permlane32_swap_b32_e32 v160, v161
	v_max_f32_e32 v161, v161, v161
	v_max_f32_e32 v160, v160, v160
	v_max_f32_e32 v160, v160, v161
	v_sub_f32_e32 v161, v160, v216
	v_cmp_ge_f32_e32 vcc, s14, v161
	v_max_f32_e32 v161, v216, v216
	v_max_f32_e32 v160, v161, v160
	s_waitcnt lgkmcnt(0)
	v_mfma_f32_32x32x16_bf16 v[16:31], v[172:175], v[234:237], v[16:31]
	v_sub_f32_e32 v161, v216, v160
	v_mul_f32_e32 v161, 0x3e0293ee, v161
	v_exp_f32_e32 v161, v161
	s_cmp_eq_u64 vcc, exec
	s_cselect_b64 s[4:5], -1, 0
	s_barrier
	s_waitcnt vmcnt(4)
	v_cndmask_b32_e64 v162, v161, 1.0, s[4:5]
	v_cmp_gt_f32_e32 vcc, 1.0, v162
	s_waitcnt vmcnt(3)
	ds_write_b128 v200, v[144:147] offset:16384
	s_waitcnt vmcnt(2)
	ds_write_b128 v201, v[148:151] offset:16384
	s_waitcnt vmcnt(1)
	ds_write_b128 v202, v[152:155] offset:49152
	s_waitcnt vmcnt(0)
	ds_write_b128 v203, v[156:159] offset:49152
	s_cbranch_vccz .LBB0_719
	s_and_saveexec_b64 s[18:19], s[2:3]
	ds_write_b32 v189, v162 offset:128
	s_or_b64 exec, exec, s[18:19]
	s_waitcnt lgkmcnt(0)
	v_add_u32_e32 v156, v191, v190
	ds_read_b128 v[144:147], v156 offset:224
	ds_read_b128 v[148:151], v156 offset:192
	ds_read_b128 v[152:155], v156 offset:160
	ds_read_b128 v[156:159], v156 offset:128
	s_waitcnt lgkmcnt(3)
	v_pk_mul_f32 v[12:13], v[12:13], v[144:145]
	s_waitcnt lgkmcnt(2)
	v_pk_mul_f32 v[8:9], v[8:9], v[148:149]
	s_waitcnt lgkmcnt(1)
	v_pk_mul_f32 v[4:5], v[4:5], v[152:153]
	v_pk_mul_f32 v[14:15], v[14:15], v[146:147]
	v_pk_mul_f32 v[10:11], v[10:11], v[150:151]
	v_pk_mul_f32 v[6:7], v[6:7], v[154:155]
	s_waitcnt lgkmcnt(0)
	v_pk_mul_f32 v[2:3], v[2:3], v[158:159]
	v_pk_mul_f32 v[0:1], v[0:1], v[156:157]
	v_pk_mul_f32 v[60:61], v[60:61], v[144:145]
	v_pk_mul_f32 v[56:57], v[56:57], v[148:149]
	v_pk_mul_f32 v[52:53], v[52:53], v[152:153]
	v_pk_mul_f32 v[62:63], v[62:63], v[146:147]
	v_pk_mul_f32 v[58:59], v[58:59], v[150:151]
	v_pk_mul_f32 v[54:55], v[54:55], v[154:155]
	v_pk_mul_f32 v[50:51], v[50:51], v[158:159]
	v_pk_mul_f32 v[48:49], v[48:49], v[156:157]
	v_pk_mul_f32 v[44:45], v[44:45], v[144:145]
	v_pk_mul_f32 v[40:41], v[40:41], v[148:149]
	v_pk_mul_f32 v[36:37], v[36:37], v[152:153]
	v_pk_mul_f32 v[46:47], v[46:47], v[146:147]
	v_pk_mul_f32 v[42:43], v[42:43], v[150:151]
	v_pk_mul_f32 v[38:39], v[38:39], v[154:155]
	v_pk_mul_f32 v[34:35], v[34:35], v[158:159]
	v_pk_mul_f32 v[32:33], v[32:33], v[156:157]
	v_pk_mul_f32 v[28:29], v[28:29], v[144:145]
	v_pk_mul_f32 v[24:25], v[24:25], v[148:149]
	v_pk_mul_f32 v[20:21], v[20:21], v[152:153]
	v_pk_mul_f32 v[30:31], v[30:31], v[146:147]
	v_pk_mul_f32 v[26:27], v[26:27], v[150:151]
	v_pk_mul_f32 v[22:23], v[22:23], v[154:155]
	v_pk_mul_f32 v[18:19], v[18:19], v[158:159]
	v_pk_mul_f32 v[16:17], v[16:17], v[156:157]
